# work balance: input-projection GEMM sample-row items all go to workgroups 128-255 (one tile fewer); plus attention epilogue store widening and sample units on even workgroups
# speedup vs baseline: 1.0212x; 1.0045x over previous
; #define LAS __attribute__((address_space(3)))
; template <int MODE>
; __device__ __forceinline__ void small_gemm(const bf16_t* A, const bf16_t* Bt, int Npos, int K, const LAS unsigned long long* eap, LAS unsigned char* lds, int wg, int G, int wid, int lane) {
;     const int fr = lane & 15, fq = lane >> 4, ncg = (MODE == 0 ? (ABIN + 63) / 64 : Npos / 64), nunits = (TS / 16) * ncg, KW = K / 8;
;     LAS f32x4* part = (LAS f32x4*)lds;
;     for (int u = wg; u < nunits; u += G) {
;         const int rb = u % (TS / 16), cgp = u / (TS / 16), r0 = TP + rb * 16, p0 = cgp * 64;
.LBB0_441:
	s_andn2_b64 vcc, exec, s[0:1]
	v_readlane_b32 s25, v245, 10
	s_cbranch_vccnz .LBB0_458
	s_lshr_b32 s2, s48, 3
	v_lshrrev_b32_e32 v0, 1, v166
	s_mul_i32 s12, s2, s61
	v_and_b32_e32 v76, 24, v0
	v_mul_u32_u24_e64 v0, s48, 48
	s_ashr_i32 s13, s12, 31
	s_lshl_b32 s4, s61, 12
	v_lshlrev_b32_e32 v0, 1, v0
	s_waitcnt vmcnt(16) lgkmcnt(0)
	v_mov_b32_e32 v1, v161
	s_cmp_lt_u32 s76, 64
	v_and_b32_e32 v160, 48, v166
	v_lshl_add_u64 v[0:1], s[62:63], 0, v[0:1]
	v_or_b32_e32 v79, 0x8000, v165
	s_waitcnt vmcnt(0)
	v_lshl_add_u32 v94, v164, 4, 0
	s_cselect_b64 s[0:1], -1, 0
	v_cmp_gt_u32_e64 s[38:39], 32, v164
	v_cmp_lt_u32_e64 s[40:41], 31, v164
	v_cmp_lt_u32_e64 s[42:43], 12, v165
	v_add_u32_e32 v78, -13, v165
	s_lshl_b64 s[18:19], s[12:13], 1
	v_lshl_add_u64 v[80:81], s[70:71], 0, v[160:161]
	s_lshl_b32 s12, s48, 1
	v_lshl_add_u64 v[82:83], s[62:63], 0, v[160:161]
	v_lshl_add_u64 v[84:85], v[0:1], 0, v[160:161]
	s_add_i32 s13, s94, 0xffffff80
	s_cmp_lt_i32 s13, 0
	s_cbranch_scc1 .LBB0_457
	s_branch .LBB0_445
	s_nop 0
	s_nop 0
	s_nop 0
	s_nop 0
	s_nop 0
	s_nop 0
	s_nop 0
	s_nop 0
	s_nop 0
	s_nop 0
	s_nop 0
	s_nop 0
	s_nop 0

; template <int MODE>
; __device__ __forceinline__ void small_gemm(const bf16_t* A, const bf16_t* Bt, int Npos, int K, const LAS unsigned long long* eap, LAS unsigned char* lds, int wg, int G, int wid, int lane) {
;     ...
;     for (int u = wg; u < nunits; u += G) {
;         const int rb = u % (TS / 16), cgp = u / (TS / 16), r0 = TP + rb * 16, p0 = cgp * 64;
.LBB0_444:
	s_addk_i32 s13, 0x80
	s_cmpk_lt_i32 s13, 0x1c8
	s_barrier
	s_cbranch_scc0 .LBB0_457
